# SSD out: SIMD-partner stagger: waves 4-7 enter the direction-0 MFMA block ~1000 cycles (s_sleep 16) after waves 0-3 so one wave's MFMA stages run beside the other's VALU stages; on top of v52
# baseline (speedup 1.0000x reference)
; #define LAS __attribute__((address_space(3)))
; template <class Wait>
; __device__ __forceinline__ void out_unit(Frame& F, const Ptrs& P, int b, int c, int g, const Wait& wait) {
;     ...
;     f32x16 y[2][2];
; #pragma unroll
;     for (int i = 0; i < 2; ++i)
; #pragma unroll
;         for (int j = 0; j < 2; ++j) y[i][j] = f32x16{};
; #pragma unroll
;     for (int ks = 0; ks < 8; ++ks) { const int chn = 2 * ks + hi;
;         const bf16x8 c0 = *(const LAS bf16x8*)(crow0 + ((chn ^ (q0 & 15)) * 16)), c1 = *(const LAS bf16x8*)(crow1 + ((chn ^ (q1 & 15)) * 16));
;         y[0][0] = __builtin_amdgcn_mfma_f32_32x32x16_bf16(A0[0][ks], c0, y[0][0], 0, 0, 0); y[0][1] = __builtin_amdgcn_mfma_f32_32x32x16_bf16(A0[0][ks], c1, y[0][1], 0, 0, 0);
;         y[1][0] = __builtin_amdgcn_mfma_f32_32x32x16_bf16(A0[1][ks], c0, y[1][0], 0, 0, 0); y[1][1] = __builtin_amdgcn_mfma_f32_32x32x16_bf16(A0[1][ks], c1, y[1][1], 0, 0, 0); }
.LBB0_742:
	s_cmp_eq_u64 s[20:21], 0
	s_cbranch_scc1 .Lstag_skip
	s_sleep 16
